# rebalance dilated units between compression and non-compression workgroups
# baseline (speedup 1.0000x reference)
.LBB0_1389:
	v_readlane_b32 s0, v253, 2
	s_cmpk_gt_i32 s0, 0x2ff
	v_readlane_b32 s1, v253, 3
	s_cbranch_scc1 .LBB0_1411
	v_lshrrev_b32_e32 v4, 5, v138
	v_mov_b32_e32 v101, 0
	v_lshlrev_b32_e32 v98, 4, v4
	v_mov_b32_e32 v99, v101
	v_and_b32_e32 v1, 31, v0
	s_waitcnt lgkmcnt(0)
	v_lshl_add_u64 v[2:3], s[26:27], 0, v[98:99]
	s_mov_b64 s[0:1], 0x8e00000
	v_lshl_add_u64 v[102:103], v[2:3], 0, s[0:1]
	v_lshlrev_b32_e32 v3, 10, v4
	v_lshlrev_b32_e32 v5, 4, v1
	s_add_u32 s10, s26, 0xee00000
	v_lshlrev_b32_e32 v2, 3, v0
	v_add3_u32 v99, 0, v3, v5
	v_lshlrev_b32_e32 v3, 1, v0
	s_addc_u32 s11, s27, 0
	v_and_b32_e32 v2, 24, v2
	v_and_b32_e32 v3, 32, v3
	v_lshlrev_b32_e32 v6, 4, v0
	s_add_u32 s22, s26, 0xbe00000
	v_add3_u32 v3, 0, v3, v2
	v_lshlrev_b32_e32 v5, 8, v4
	v_and_b32_e32 v6, 0xc0, v6
	v_lshlrev_b32_e32 v100, 1, v1
	s_addc_u32 s23, s27, 0
	v_add3_u32 v105, v3, v5, v6
	v_lshlrev_b32_e32 v113, 2, v4
	v_lshl_add_u64 v[4:5], s[26:27], 0, v[100:101]
	s_mov_b64 s[0:1], 0x100000
	s_add_u32 s24, s26, 0xa600000
	v_lshl_add_u64 v[106:107], v[4:5], 0, s[0:1]
	v_readlane_b32 s0, v253, 2
	s_addc_u32 s25, s27, 0
	v_lshrrev_b32_e32 v104, 2, v138
	s_mov_b32 s13, 0
	v_cmp_gt_u32_e64 s[2:3], 32, v138
	v_or_b32_e32 v114, 1, v113
	v_or_b32_e32 v115, 2, v113
	v_or_b32_e32 v116, 3, v113
	v_or_b32_e32 v117, 8, v113
	v_or_b32_e32 v118, 9, v113
	v_or_b32_e32 v119, 10, v113
	v_or_b32_e32 v120, 11, v113
	v_or_b32_e32 v121, 16, v113
	v_or_b32_e32 v122, 17, v113
	v_or_b32_e32 v123, 18, v113
	v_or_b32_e32 v124, 19, v113
	v_or_b32_e32 v125, 24, v113
	v_or_b32_e32 v126, 25, v113
	v_or_b32_e32 v127, 26, v113
	v_or_b32_e32 v128, 27, v113
	v_sub_u32_e32 v129, v1, v113
	v_lshlrev_b32_e32 v100, 1, v2
	s_mov_b32 s30, 0xff61b1e6
	s_movk_i32 s31, 0x81
	s_movk_i32 s33, 0xff7e
	s_mov_b32 s34, 0xefa18f08
	s_mov_b32 s35, 0x41000000
	s_movk_i32 s36, 0x7fff
	v_mov_b32_e32 v130, 0xf149f2ca
	v_mov_b32_e32 v131, 0xff61b1e6
	s_mov_b32 s37, s0
	s_mov_b32 s98, s70
	s_movk_i32 s99, 0x2ff
	s_cmpk_lg_i32 s70, 0x100
	s_cbranch_scc1 .Ldil_bal_done
	s_movk_i32 s98, 0x80
	s_cmpk_lt_i32 s0, 0x80
	s_cselect_b32 s99, 0xff, s99
	s_cselect_b32 s1, 0, 0x80
	s_add_i32 s37, s0, s1
.Ldil_bal_done:
	v_readlane_b32 s1, v253, 3
	s_branch .LBB0_1392
.LBB0_1391:
	s_or_b64 exec, exec, s[4:5]
	v_lshl_add_u32 v46, v113, 2, s39
	s_waitcnt lgkmcnt(0)
	ds_read_b128 v[36:39], v46 offset:128
	ds_read_b128 v[40:43], v46 offset:160
	v_lshl_add_u64 v[34:35], s[0:1], 1, v[106:107]
	s_and_b64 s[0:1], s[16:17], exec
	v_or_b32_e32 v44, s38, v113
	s_cselect_b32 s4, 9, 11
	s_and_b64 s[0:1], s[14:15], exec
	v_ashrrev_i32_e32 v45, 31, v44
	s_waitcnt lgkmcnt(1)
	v_mul_f32_e32 v18, v18, v36
	s_cselect_b32 s0, 7, s4
	v_bfe_u32 v47, v18, 16, 1
	v_lshlrev_b64 v[44:45], s0, v[44:45]
	v_add3_u32 v18, v18, v47, s36
	v_lshl_add_u64 v[44:45], v[34:35], 0, v[44:45]
	v_mul_f32_e32 v2, v2, v36
	global_store_short_d16_hi v[44:45], v18, off
	v_bfe_u32 v18, v2, 16, 1
	v_add3_u32 v2, v2, v18, s36
	global_store_short_d16_hi v[44:45], v2, off offset:64
	v_or_b32_e32 v44, s38, v114
	v_mul_f32_e32 v2, v19, v37
	v_ashrrev_i32_e32 v45, 31, v44
	v_bfe_u32 v18, v2, 16, 1
	v_add3_u32 v2, v2, v18, s36
	v_lshlrev_b64 v[18:19], s0, v[44:45]
	v_lshl_add_u64 v[18:19], v[34:35], 0, v[18:19]
	global_store_short_d16_hi v[18:19], v2, off
	v_mul_f32_e32 v2, v3, v37
	v_bfe_u32 v3, v2, 16, 1
	v_add3_u32 v2, v2, v3, s36
	global_store_short_d16_hi v[18:19], v2, off offset:64
	v_or_b32_e32 v2, s38, v115
	v_ashrrev_i32_e32 v3, 31, v2
	v_mul_f32_e32 v18, v20, v38
	v_bfe_u32 v19, v18, 16, 1
	v_lshlrev_b64 v[2:3], s0, v[2:3]
	v_add3_u32 v18, v18, v19, s36
	v_lshl_add_u64 v[2:3], v[34:35], 0, v[2:3]
	v_mul_f32_e32 v4, v4, v38
	global_store_short_d16_hi v[2:3], v18, off
	v_bfe_u32 v18, v4, 16, 1
	v_add3_u32 v4, v4, v18, s36
	global_store_short_d16_hi v[2:3], v4, off offset:64
	v_or_b32_e32 v2, s38, v116
	v_ashrrev_i32_e32 v3, 31, v2
	v_mul_f32_e32 v4, v21, v39
	v_bfe_u32 v18, v4, 16, 1
	v_lshlrev_b64 v[2:3], s0, v[2:3]
	v_add3_u32 v4, v4, v18, s36
	v_lshl_add_u64 v[2:3], v[34:35], 0, v[2:3]
	global_store_short_d16_hi v[2:3], v4, off
	v_mul_f32_e32 v4, v5, v39
	v_bfe_u32 v5, v4, 16, 1
	v_add3_u32 v4, v4, v5, s36
	global_store_short_d16_hi v[2:3], v4, off offset:64
	v_or_b32_e32 v2, s38, v117
	v_ashrrev_i32_e32 v3, 31, v2
	s_waitcnt lgkmcnt(0)
	v_mul_f32_e32 v4, v22, v40
	v_bfe_u32 v5, v4, 16, 1
	v_lshlrev_b64 v[2:3], s0, v[2:3]
	v_add3_u32 v4, v4, v5, s36
	v_lshl_add_u64 v[2:3], v[34:35], 0, v[2:3]
	global_store_short_d16_hi v[2:3], v4, off
	v_mul_f32_e32 v4, v6, v40
	v_bfe_u32 v5, v4, 16, 1
	v_add3_u32 v4, v4, v5, s36
	global_store_short_d16_hi v[2:3], v4, off offset:64
	v_or_b32_e32 v2, s38, v118
	v_ashrrev_i32_e32 v3, 31, v2
	v_mul_f32_e32 v4, v23, v41
	v_bfe_u32 v5, v4, 16, 1
	v_lshlrev_b64 v[2:3], s0, v[2:3]
	v_add3_u32 v4, v4, v5, s36
	v_lshl_add_u64 v[2:3], v[34:35], 0, v[2:3]
	global_store_short_d16_hi v[2:3], v4, off
	v_mul_f32_e32 v4, v7, v41
	v_bfe_u32 v5, v4, 16, 1
	v_add3_u32 v4, v4, v5, s36
	global_store_short_d16_hi v[2:3], v4, off offset:64
	v_or_b32_e32 v2, s38, v119
	v_ashrrev_i32_e32 v3, 31, v2
	v_mul_f32_e32 v4, v24, v42
	v_bfe_u32 v5, v4, 16, 1
	v_lshlrev_b64 v[2:3], s0, v[2:3]
	v_add3_u32 v4, v4, v5, s36
	v_lshl_add_u64 v[2:3], v[34:35], 0, v[2:3]
	global_store_short_d16_hi v[2:3], v4, off
	v_mul_f32_e32 v4, v8, v42
	v_bfe_u32 v5, v4, 16, 1
	v_add3_u32 v4, v4, v5, s36
	global_store_short_d16_hi v[2:3], v4, off offset:64
	v_or_b32_e32 v2, s38, v120
	v_ashrrev_i32_e32 v3, 31, v2
	v_mul_f32_e32 v4, v25, v43
	v_lshlrev_b64 v[2:3], s0, v[2:3]
	v_bfe_u32 v5, v4, 16, 1
	v_lshl_add_u64 v[6:7], v[34:35], 0, v[2:3]
	v_mul_f32_e32 v2, v9, v43
	v_add3_u32 v4, v4, v5, s36
	v_bfe_u32 v3, v2, 16, 1
	global_store_short_d16_hi v[6:7], v4, off
	v_add3_u32 v8, v2, v3, s36
	ds_read_b128 v[2:5], v46 offset:192
	v_or_b32_e32 v18, s38, v121
	global_store_short_d16_hi v[6:7], v8, off offset:64
	v_ashrrev_i32_e32 v19, 31, v18
	ds_read_b128 v[6:9], v46 offset:224
	s_waitcnt lgkmcnt(1)
	v_mul_f32_e32 v20, v26, v2
	v_mul_f32_e32 v2, v10, v2
	v_bfe_u32 v21, v20, 16, 1
	v_lshlrev_b64 v[18:19], s0, v[18:19]
	v_bfe_u32 v10, v2, 16, 1
	v_add3_u32 v20, v20, v21, s36
	v_lshl_add_u64 v[18:19], v[34:35], 0, v[18:19]
	v_add3_u32 v2, v2, v10, s36
	global_store_short_d16_hi v[18:19], v20, off
	global_store_short_d16_hi v[18:19], v2, off offset:64
	v_or_b32_e32 v18, s38, v122
	v_ashrrev_i32_e32 v19, 31, v18
	v_mul_f32_e32 v2, v27, v3
	v_bfe_u32 v10, v2, 16, 1
	v_lshlrev_b64 v[18:19], s0, v[18:19]
	v_add3_u32 v2, v2, v10, s36
	v_lshl_add_u64 v[18:19], v[34:35], 0, v[18:19]
	global_store_short_d16_hi v[18:19], v2, off
	v_mul_f32_e32 v2, v11, v3
	v_bfe_u32 v3, v2, 16, 1
	v_add3_u32 v2, v2, v3, s36
	global_store_short_d16_hi v[18:19], v2, off offset:64
	v_or_b32_e32 v2, s38, v123
	v_ashrrev_i32_e32 v3, 31, v2
	v_mul_f32_e32 v10, v28, v4
	v_bfe_u32 v11, v10, 16, 1
	v_lshlrev_b64 v[2:3], s0, v[2:3]
	v_add3_u32 v10, v10, v11, s36
	v_lshl_add_u64 v[2:3], v[34:35], 0, v[2:3]
	v_mul_f32_e32 v4, v12, v4
	global_store_short_d16_hi v[2:3], v10, off
	v_bfe_u32 v10, v4, 16, 1
	v_add3_u32 v4, v4, v10, s36
	global_store_short_d16_hi v[2:3], v4, off offset:64
	v_or_b32_e32 v2, s38, v124
	v_ashrrev_i32_e32 v3, 31, v2
	v_mul_f32_e32 v4, v29, v5
	v_bfe_u32 v10, v4, 16, 1
	v_lshlrev_b64 v[2:3], s0, v[2:3]
	v_add3_u32 v4, v4, v10, s36
	v_lshl_add_u64 v[2:3], v[34:35], 0, v[2:3]
	global_store_short_d16_hi v[2:3], v4, off
	v_mul_f32_e32 v4, v13, v5
	v_bfe_u32 v5, v4, 16, 1
	v_add3_u32 v4, v4, v5, s36
	global_store_short_d16_hi v[2:3], v4, off offset:64
	v_or_b32_e32 v2, s38, v125
	v_ashrrev_i32_e32 v3, 31, v2
	s_waitcnt lgkmcnt(0)
	v_mul_f32_e32 v4, v30, v6
	v_bfe_u32 v5, v4, 16, 1
	v_lshlrev_b64 v[2:3], s0, v[2:3]
	v_add3_u32 v4, v4, v5, s36
	v_lshl_add_u64 v[2:3], v[34:35], 0, v[2:3]
	global_store_short_d16_hi v[2:3], v4, off
	v_mul_f32_e32 v4, v14, v6
	v_bfe_u32 v5, v4, 16, 1
	v_add3_u32 v4, v4, v5, s36
	global_store_short_d16_hi v[2:3], v4, off offset:64
	v_or_b32_e32 v2, s38, v126
	v_ashrrev_i32_e32 v3, 31, v2
	v_mul_f32_e32 v4, v31, v7
	v_bfe_u32 v5, v4, 16, 1
	v_lshlrev_b64 v[2:3], s0, v[2:3]
	v_add3_u32 v4, v4, v5, s36
	v_lshl_add_u64 v[2:3], v[34:35], 0, v[2:3]
	global_store_short_d16_hi v[2:3], v4, off
	v_mul_f32_e32 v4, v15, v7
	v_bfe_u32 v5, v4, 16, 1
	v_add3_u32 v4, v4, v5, s36
	global_store_short_d16_hi v[2:3], v4, off offset:64
	v_or_b32_e32 v2, s38, v127
	v_ashrrev_i32_e32 v3, 31, v2
	v_mul_f32_e32 v4, v32, v8
	v_bfe_u32 v5, v4, 16, 1
	v_lshlrev_b64 v[2:3], s0, v[2:3]
	v_add3_u32 v4, v4, v5, s36
	v_lshl_add_u64 v[2:3], v[34:35], 0, v[2:3]
	global_store_short_d16_hi v[2:3], v4, off
	v_mul_f32_e32 v4, v16, v8
	v_bfe_u32 v5, v4, 16, 1
	v_add3_u32 v4, v4, v5, s36
	global_store_short_d16_hi v[2:3], v4, off offset:64
	v_or_b32_e32 v2, s38, v128
	v_ashrrev_i32_e32 v3, 31, v2
	v_mul_f32_e32 v4, v33, v9
	v_bfe_u32 v5, v4, 16, 1
	v_lshlrev_b64 v[2:3], s0, v[2:3]
	v_add3_u32 v4, v4, v5, s36
	v_lshl_add_u64 v[2:3], v[34:35], 0, v[2:3]
	global_store_short_d16_hi v[2:3], v4, off
	v_mul_f32_e32 v4, v17, v9
	v_bfe_u32 v5, v4, 16, 1
	s_add_i32 s37, s98, s37
	v_add3_u32 v4, v4, v5, s36
	s_cmp_gt_i32 s37, s99
	global_store_short_d16_hi v[2:3], v4, off offset:64
	s_barrier
	s_cbranch_scc1 .LBB0_1411
